# speedup vs baseline: 1.0002x; 1.0002x over previous
; __device__ __forceinline__ float b2f(u16 b) { return __uint_as_float(((unsigned)b) << 16); }
; __device__ __forceinline__ void scan_pc(const Params& p, int j, const u16* R, const u16* K, const u16* V, u16* Y, u16* YB) {
;     ...
;     auto load_yold = [&](int c) {
;       _Pragma("unroll") for (int jj = 0; jj < 4; ++jj) yo[jj] = b2f(ldo<u16>(Yw, (unsigned)(offK0[jj] + c * dK)));
;     };
;     ...
;     else { stage_b(0); if (ymode == 1) load_yold(0); }
.LBB0_2710:
	s_or_b64 exec, exec, s[26:27]
	s_cmp_lg_u32 s29, 1
	s_cbranch_scc1 .LBB0_2768
	global_load_ushort v230, v154, s[66:67]
	global_load_ushort v231, v157, s[66:67]
	global_load_ushort v232, v155, s[66:67]
	global_load_ushort v233, v156, s[66:67]
	s_waitcnt vmcnt(3)
	v_lshlrev_b32_e32 v87, 16, v230
	s_waitcnt vmcnt(2)
	v_lshlrev_b32_e32 v88, 16, v231
	s_waitcnt vmcnt(1)
	v_lshlrev_b32_e32 v86, 16, v232
	s_waitcnt vmcnt(0)
	v_lshlrev_b32_e32 v89, 16, v233

; __device__ __forceinline__ float b2f(u16 b) { return __uint_as_float(((unsigned)b) << 16); }
; #define MFMA4(a, b, c) __builtin_amdgcn_mfma_f32_16x16x16bf16_1k(a, b, c, 0, 0, 0)
; __device__ __forceinline__ s4 pack4v(f32x4 v) { return pack4(v[0], v[1], v[2], v[3]); }
; __device__ __forceinline__ void scan_pc(const Params& p, int j, const u16* R, const u16* K, const u16* V, u16* Y, u16* YB) {
;     ...
;       _Pragma("unroll") for (int jj = 0; jj < 4; ++jj) yo[jj] = b2f(ldo<u16>(Yw, (unsigned)(offK0[jj] + c * dK)));
;     ...
;       const u16* IMG = shm + (c % 3) * IMG_ELEMS;
;       const u16* MM = shm + 4 * IMG_ELEMS + (c & 1) * MM_ELEMS;
;       s4 vb = *reinterpret_cast<const s4*>(IMG + IMG_VT + (w4 * 16 + fr) * XK_LD + fq * 4);
;       f32x4 z4 = {0.f, 0.f, 0.f, 0.f};
;       const float* PL = reinterpret_cast<const float*>(IMG + IMG_PL);
;       float4 iv = *reinterpret_cast<const float4*>(PL + 192 + fq * 4);
;       f32x4 rhs = z4;
;       f32x4 y = MFMA4(*reinterpret_cast<const s4*>(MM + (3 * 16 + fr) * XK_LD + fq * 4), vb, z4);
;       _Pragma("unroll") for (int kb = 0; kb < 4; ++kb) {
;         rhs = MFMA4(*reinterpret_cast<const s4*>(IMG + (0 * 16 + fr) * XT_LD + kb * 16 + fq * 4), Zb[kb], rhs);
;         y = MFMA4(*reinterpret_cast<const s4*>(IMG + (1 * 16 + fr) * XT_LD + kb * 16 + fq * 4), Zb[kb], y);
;       }
;       rhs[0] *= iv.x; rhs[1] *= iv.y; rhs[2] *= iv.z; rhs[3] *= iv.w;
;       rhs = MFMA4(*reinterpret_cast<const s4*>(MM + (1 * 16 + fr) * XK_LD + fq * 4), vb, rhs);
;       f32x4 u = MFMA4(*reinterpret_cast<const s4*>(MM + (0 * 16 + fr) * XK_LD + fq * 4), pack4v(rhs), z4);
;       y = MFMA4(*reinterpret_cast<const s4*>(MM + (2 * 16 + fr) * XK_LD + fq * 4), pack4v(u), y);
;       s4 ub = pack4(u[0] * iv.x, u[1] * iv.y, u[2] * iv.z, u[3] * iv.w);
;       _Pragma("unroll") for (int kb = 0; kb < 4; ++kb) {
;         Z[kb] = MFMA4(*reinterpret_cast<const s4*>(IMG + IMG_XK + (0 * 64 + kb * 16 + fr) * XK_LD + fq * 4), ub, Z[kb]);
;         Z[kb] = MFMA4(*reinterpret_cast<const s4*>(IMG + IMG_XK + (1 * 64 + kb * 16 + fr) * XK_LD + fq * 4), vb, Z[kb]);
;         float4 pl = *reinterpret_cast<const float4*>(PL + kb * 16 + fq * 4);
;         Z[kb][0] *= pl.x; Z[kb][1] *= pl.y; Z[kb][2] *= pl.z; Z[kb][3] *= pl.w;
;         Zb[kb] = pack4v(Z[kb]);
;       }
.LBB0_2720:
	s_mul_hi_u32 s26, s28, 0xaaaaaaab
	s_lshr_b32 s26, s26, 1
	s_mul_i32 s26, s26, 3
	s_sub_i32 s75, 1, s26
	v_lshlrev_b32_e32 v179, 1, v97
	s_and_saveexec_b64 s[26:27], s[10:11]
	s_xor_b64 s[26:27], exec, s[26:27]
	s_cbranch_execz .LBB0_2739
	s_mov_b32 s30, 0xaaaaaaab
	v_mul_hi_u32 v50, v90, s30
	v_lshrrev_b32_e32 v50, 1, v50
	v_mad_u64_u32 v[50:51], s[30:31], v50, -3, v[90:91]
	v_mad_u32_u24 v58, v50, s80, 0
	v_add3_u32 v50, v58, v127, v179
	ds_read_b64 v[70:71], v50 offset:14336
	v_lshl_add_u32 v50, v97, 2, v58
	ds_read_b128 v[66:69], v50 offset:17664
	v_add3_u32 v50, v58, v146, v179
	ds_read2_b64 v[60:63], v145 offset0:160 offset1:240
	ds_read2_b64 v[194:197], v50 offset1:4
	v_add_u32_e32 v59, 0x800, v50
	ds_read2_b64 v[202:205], v59 offset0:32 offset1:36
	s_waitcnt lgkmcnt(2)
	v_mfma_f32_16x16x16_bf16 v[92:95], v[62:63], v[70:71], 0
	v_add3_u32 v91, v58, v144, v133
	v_add_u32_e32 v193, 0x2c00, v91
	v_readlane_b32 s76, v247, 14
	s_waitcnt lgkmcnt(1)
	v_mfma_f32_16x16x16_bf16 v[198:201], v[194:195], v[64:65], 0
	v_readlane_b32 s77, v247, 15
	v_readlane_b32 s78, v247, 16
	v_readlane_b32 s79, v247, 17
	s_waitcnt lgkmcnt(0)
	v_mfma_f32_16x16x16_bf16 v[62:65], v[202:203], v[64:65], v[92:95]
	s_mov_b32 s77, s76
	s_mov_b32 s78, s76
	s_mov_b32 s79, s76
	v_mfma_f32_16x16x16_bf16 v[92:95], v[196:197], v[56:57], v[198:201]
	ds_read2_b64 v[194:197], v50 offset0:8 offset1:12
	v_add_u32_e32 v50, 0x2000, v91
	v_writelane_b32 v247, s76, 14
	s_waitcnt lgkmcnt(0)
	v_mfma_f32_16x16x16_bf16 v[92:95], v[194:195], v[52:53], v[92:95]
	ds_read2_b64 v[198:201], v145 offset1:80
	v_writelane_b32 v247, s77, 15
	v_writelane_b32 v247, s78, 16
	v_mfma_f32_16x16x16_bf16 v[92:95], v[196:197], v[48:49], v[92:95]
	ds_read2_b64 v[194:197], v50 offset0:128 offset1:208
	v_writelane_b32 v247, s79, 17
	v_mfma_f32_16x16x16_bf16 v[62:65], v[204:205], v[56:57], v[62:65]
	s_nop 4
	v_mul_f32_e64 v94, v68, v94
	v_mul_f32_e64 v95, v69, v95
	v_pk_mul_f32 v[92:93], v[66:67], v[92:93]
	s_waitcnt lgkmcnt(1)
	s_nop 0
	v_mfma_f32_16x16x16_bf16 v[92:95], v[200:201], v[70:71], v[92:95]
	s_nop 7
	v_cvt_pk_bf16_f32 v50, v92, v93
	v_cvt_pk_bf16_f32 v51, v94, v95
	s_nop 1
	v_mfma_f32_16x16x16_bf16 v[92:95], v[198:199], v[50:51], 0
	ds_read2_b64 v[198:201], v59 offset0:40 offset1:44
	s_nop 6
	v_pk_mul_f32 v[50:51], v[66:67], v[92:93]
	v_pk_mul_f32 v[54:55], v[68:69], v[94:95]
	ds_read2_b64 v[66:69], v193 offset0:64 offset1:144
	v_cvt_pk_bf16_f32 v180, v50, v51
	v_cvt_pk_bf16_f32 v181, v54, v55
	s_waitcnt lgkmcnt(1)
	v_mfma_f32_16x16x16_bf16 v[50:53], v[198:199], v[52:53], v[62:65]
	v_add_u32_e32 v193, v58, v112
	v_add_u32_e32 v54, 0x2800, v91
	v_cvt_pk_bf16_f32 v202, v92, v93
	v_mfma_f32_16x16x16_bf16 v[40:43], v[194:195], v[180:181], v[40:43]
	v_cvt_pk_bf16_f32 v203, v94, v95
	v_mfma_f32_16x16x16_bf16 v[194:197], v[196:197], v[180:181], v[44:47]
	ds_read_b128 v[56:59], v193 offset:16896
	s_nop 1
	ds_read_b128 v[44:47], v193 offset:16960
	s_waitcnt lgkmcnt(2)
	v_mfma_f32_16x16x16_bf16 v[40:43], v[66:67], v[70:71], v[40:43]
	ds_read2_b64 v[64:67], v54 offset0:32 offset1:112
	v_add_u32_e32 v54, 0x3000, v91
	v_add_u32_e32 v91, s74, v166
	v_mfma_f32_16x16x16_bf16 v[92:95], v[200:201], v[48:49], v[50:53]
	ds_read2_b64 v[198:201], v54 offset0:96 offset1:176
	s_nop 1
	ds_read_b128 v[52:55], v193 offset:17024
	ds_read_b128 v[48:51], v193 offset:17088
	v_mfma_f32_16x16x16_bf16 v[92:95], v[60:61], v[202:203], v[92:95]
	s_waitcnt lgkmcnt(3)
	v_mfma_f32_16x16x16_bf16 v[32:35], v[64:65], v[180:181], v[32:35]
	v_mfma_f32_16x16x16_bf16 v[36:39], v[66:67], v[180:181], v[36:39]
	s_andn2_b64 vcc, exec, s[20:21]
	s_cbranch_vccnz .Lyold_done_a
	s_waitcnt vmcnt(0)
	v_lshlrev_b32_e32 v87, 16, v230
	v_lshlrev_b32_e32 v88, 16, v231
	v_lshlrev_b32_e32 v86, 16, v232
	v_lshlrev_b32_e32 v89, 16, v233
; #define MFMA4(a, b, c) __builtin_amdgcn_mfma_f32_16x16x16bf16_1k(a, b, c, 0, 0, 0)
; __device__ __forceinline__ void scan_pc(const Params& p, int j, const u16* R, const u16* K, const u16* V, u16* Y, u16* YB) {
;     ...
;       u16* IMG = shm + (c % 3) * IMG_ELEMS;
;       u16* MM = shm + 4 * IMG_ELEMS + (c & 1) * MM_ELEMS;
;       int ai = (w4 < 2) ? 0 : 1, bi = (w4 & 1) ? 3 : 2;
;       f32x4 mt = {0.f, 0.f, 0.f, 0.f}, nc = {0.f, 0.f, 0.f, 0.f};
;       _Pragma("unroll") for (int kb = 0; kb < 4; ++kb) {
;         s4 xa = *reinterpret_cast<const s4*>(IMG + (ai * 16 + fr) * XT_LD + kb * 16 + fq * 4);
;         s4 xb = *reinterpret_cast<const s4*>(IMG + (bi * 16 + fr) * XT_LD + kb * 16 + fq * 4);
;         mt = MFMA4(xb, xa, mt);
;         if (w4 == 0) nc = MFMA4(xa, xb, nc);
;       }
;       float* SSQ = reinterpret_cast<float*>(IMG + IMG_PL) + 128;
;       float inv_t = rsqrtf(fmaxf((SSQ[fr] + SSQ[16 + fr]) + (SSQ[32 + fr] + SSQ[48 + fr]), 1e-24f));
;       if (w4 == 3) SSQ[64 + fr] = inv_t;
;       float ivr = (w4 < 2) ? inv_t : 1.f;
;       float sc_[4];
;       _Pragma("unroll") for (int jj = 0; jj < 4; ++jj) {
;         float ivj = __builtin_bit_cast(float, __builtin_amdgcn_ds_bpermute(((lane & 48) | (fq * 4 + jj)) << 2, __builtin_bit_cast(int, inv_t)));
;         sc_[jj] = ivr * (((w4 & 1) == 0) ? ivj : 1.f);
;         mt[jj] *= sc_[jj] * keepm[jj];
;       }
;       if (w4 == 0) {
;         _Pragma("unroll") for (int jj = 0; jj < 4; ++jj) nc[jj] *= sc_[jj] * keepn[jj];
;         f32x4 z4 = {0.f, 0.f, 0.f, 0.f};
;         s4 pN = pack4v(nc), pNT = pack4v(mt);
;         f32x4 n2 = MFMA4(pNT, pN, z4);
;         f32x4 n2t = MFMA4(pN, pNT, z4);
;         s4 pN2 = pack4v(n2), pN2T = pack4v(n2t);
;         f32x4 n4 = MFMA4(pN2T, pN2, z4);
;         f32x4 n4t = MFMA4(pN2, pN2T, z4);
;         s4 pN4 = pack4v(n4), pN4T = pack4v(n4t);
;         f32x4 n8 = MFMA4(pN4T, pN4, z4);
;         s4 pN8 = pack4v(n8);
;         f32x4 tt = mt;
;         _Pragma("unroll") for (int jj = 0; jj < 4; ++jj) tt[jj] += diagm[jj];
;         tt = MFMA4(pN2, pack4v(tt), tt);
;         tt = MFMA4(pN4, pack4v(tt), tt);
;         tt = MFMA4(pN8, pack4v(tt), tt);
;         mt = tt;
;     ...
;       _Pragma("unroll") for (int jj = 0; jj < 4; ++jj)
;         sto<u16>(Yw, (unsigned)(offK0[jj] + c * dK), f2b(ymode == 1 ? y[jj] + yo[jj] : y[jj]));
.Lyold_done_a:
	s_nop 4
	v_add_f32_e32 v60, v87, v92
	v_cndmask_b32_e64 v92, v92, v60, s[20:21]
	v_add_f32_e32 v64, v86, v93
	v_mfma_f32_16x16x16_bf16 v[60:63], v[68:69], v[70:71], v[194:197]
	v_cvt_pk_bf16_f32 v68, v92, s0
	v_cndmask_b32_e64 v64, v93, v64, s[20:21]
	v_add_f32_e32 v65, v89, v94
	global_store_short v91, v68, s[70:71]
	v_add_u32_e32 v68, s74, v178
	v_cvt_pk_bf16_f32 v64, v64, s0
	v_cndmask_b32_e64 v65, v94, v65, s[20:21]
	global_store_short v68, v64, s[70:71]
	v_add_u32_e32 v64, s74, v177
	v_cvt_pk_bf16_f32 v65, v65, s0
	global_store_short v64, v65, s[70:71]
	v_add_f32_e32 v64, v88, v95
	s_waitcnt lgkmcnt(2)
	v_mfma_f32_16x16x16_bf16 v[32:35], v[198:199], v[70:71], v[32:35]
	v_cndmask_b32_e64 v64, v95, v64, s[20:21]
	v_add_u32_e32 v65, s74, v176
	v_cvt_pk_bf16_f32 v64, v64, s0
	v_mfma_f32_16x16x16_bf16 v[36:39], v[200:201], v[70:71], v[36:39]
	global_store_short v65, v64, s[70:71]
	v_add_u32_e32 v64, 1, v90
	v_cmp_gt_u32_e32 vcc, s2, v64
	s_and_saveexec_b64 s[62:63], vcc
	s_cbranch_execz .LBB0_2738
	v_add_u32_e32 v64, s75, v90
	v_mad_u32_u24 v91, v64, s80, 0
	v_add3_u32 v180, v91, v136, v179
	v_add3_u32 v181, v91, v134, v179
	ds_read_b64 v[92:93], v180
	ds_read_b64 v[94:95], v181
	ds_read_b64 v[206:207], v180 offset:32
	ds_read_b64 v[208:209], v181 offset:32
	ds_read_b64 v[210:211], v180 offset:64
	ds_read_b64 v[212:213], v181 offset:64
	ds_read_b64 v[214:215], v180 offset:96
	ds_read_b64 v[216:217], v181 offset:96
	v_lshl_add_u32 v218, v96, 2, v91
	v_add_u32_e32 v219, 0x4400, v218
	ds_read2_b32 v[220:221], v219 offset1:16
	ds_read2_b32 v[222:223], v219 offset0:32 offset1:48
	v_readlane_b32 s76, v247, 14
	v_readlane_b32 s77, v247, 15
	v_readlane_b32 s78, v247, 16
	v_readlane_b32 s79, v247, 17
	v_mov_b64_e32 v[68:69], s[76:77]
	s_waitcnt lgkmcnt(8)
	v_mfma_f32_16x16x16_bf16 v[64:67], v[92:93], v[94:95], 0
	v_mov_b64_e32 v[70:71], s[78:79]
	s_and_saveexec_b64 s[30:31], s[14:15]
	v_mfma_f32_16x16x16_bf16 v[68:71], v[94:95], v[92:93], 0
	s_or_b64 exec, exec, s[30:31]
	s_waitcnt lgkmcnt(6)
	v_mfma_f32_16x16x16_bf16 v[64:67], v[206:207], v[208:209], v[64:67]
	s_and_saveexec_b64 s[30:31], s[14:15]
	v_mfma_f32_16x16x16_bf16 v[68:71], v[208:209], v[206:207], v[68:71]
	s_or_b64 exec, exec, s[30:31]
	s_waitcnt lgkmcnt(4)
	v_mfma_f32_16x16x16_bf16 v[64:67], v[210:211], v[212:213], v[64:67]
	s_and_saveexec_b64 s[30:31], s[14:15]
	v_mfma_f32_16x16x16_bf16 v[68:71], v[212:213], v[210:211], v[68:71]
	s_or_b64 exec, exec, s[30:31]
	s_waitcnt lgkmcnt(2)
	v_mfma_f32_16x16x16_bf16 v[64:67], v[214:215], v[216:217], v[64:67]
	s_and_saveexec_b64 s[30:31], s[14:15]
	v_mfma_f32_16x16x16_bf16 v[68:71], v[216:217], v[214:215], v[68:71]
	s_or_b64 exec, exec, s[30:31]
	v_lshl_add_u32 v93, v96, 2, v91
	s_waitcnt lgkmcnt(0)
	v_add_f32_e32 v180, v220, v221
	v_add_f32_e32 v92, v222, v223
	v_add_f32_e32 v92, v180, v92
	v_max_f32_e32 v92, 0x179abe15, v92
	v_rsq_f32_e32 v92, v92
	s_and_saveexec_b64 s[30:31], s[16:17]
	ds_write_b32 v93, v92 offset:17664
	s_or_b64 exec, exec, s[30:31]
	ds_bpermute_b32 v93, v138, v92
	ds_bpermute_b32 v94, v139, v92
	v_cndmask_b32_e64 v95, 1.0, v92, s[6:7]
	ds_bpermute_b32 v180, v140, v92
	ds_bpermute_b32 v224, v141, v92
	s_waitcnt lgkmcnt(3)
	v_cndmask_b32_e64 v93, 1.0, v93, s[18:19]
	s_waitcnt lgkmcnt(2)
	v_cndmask_b32_e64 v94, 1.0, v94, s[18:19]
	v_mul_f32_e32 v93, v95, v93
	v_mul_f32_e32 v181, v98, v93
	v_mul_f32_e32 v94, v95, v94
	v_mul_f32_e32 v64, v64, v181
	v_mul_f32_e32 v181, v101, v94
	v_mul_f32_e32 v65, v65, v181
	s_waitcnt lgkmcnt(1)
	v_cndmask_b32_e64 v92, 1.0, v180, s[18:19]
	v_mul_f32_e32 v92, v95, v92
	v_mul_f32_e32 v180, v104, v92
	v_mul_f32_e32 v66, v66, v180
	s_waitcnt lgkmcnt(0)
	v_cndmask_b32_e64 v180, 1.0, v224, s[18:19]
	v_mul_f32_e32 v95, v95, v180
	v_mul_f32_e32 v180, v107, v95
	v_mul_f32_e32 v67, v67, v180
	s_and_saveexec_b64 s[30:31], s[14:15]
	s_cbranch_execz .LBB0_2734
	v_mul_f32_e32 v93, v99, v93
	v_mul_f32_e32 v92, v105, v92
	v_mul_f32_e32 v68, v68, v93
	v_mul_f32_e32 v93, v102, v94
	v_mul_f32_e32 v70, v70, v92
	v_mul_f32_e32 v92, v108, v95
	v_mul_f32_e32 v69, v69, v93
	v_mul_f32_e32 v71, v71, v92
	v_cvt_pk_bf16_f32 v92, v68, v69
	v_cvt_pk_bf16_f32 v93, v70, v71
	v_cvt_pk_bf16_f32 v94, v64, v65
	v_cvt_pk_bf16_f32 v95, v66, v67
	v_add_f32_e32 v64, v100, v64
	v_add_f32_e32 v65, v103, v65
	v_mfma_f32_16x16x16_bf16 v[68:71], v[94:95], v[92:93], 0
	v_add_f32_e32 v66, v106, v66
	v_add_f32_e32 v67, v109, v67
	v_mfma_f32_16x16x16_bf16 v[92:95], v[92:93], v[94:95], 0
	s_nop 4
	v_cvt_pk_bf16_f32 v180, v68, v69
	v_cvt_pk_bf16_f32 v181, v70, v71
	s_nop 0
	v_cvt_pk_bf16_f32 v92, v92, v93
	v_cvt_pk_bf16_f32 v93, v94, v95
	s_nop 1
	v_mfma_f32_16x16x16_bf16 v[68:71], v[92:93], v[180:181], 0
	v_mfma_f32_16x16x16_bf16 v[92:95], v[180:181], v[92:93], 0
	s_nop 6
	v_cvt_pk_bf16_f32 v194, v68, v69
	v_cvt_pk_bf16_f32 v195, v70, v71
	v_cvt_pk_bf16_f32 v68, v92, v93
	v_cvt_pk_bf16_f32 v69, v94, v95
	s_nop 1
	v_mfma_f32_16x16x16_bf16 v[68:71], v[68:69], v[194:195], 0
	s_nop 7
	v_cvt_pk_bf16_f32 v68, v68, v69
	v_cvt_pk_bf16_f32 v69, v70, v71
	v_cvt_pk_bf16_f32 v70, v64, v65
	v_cvt_pk_bf16_f32 v71, v66, v67
	s_nop 1
	v_mfma_f32_16x16x16_bf16 v[64:67], v[180:181], v[70:71], v[64:67]
	s_nop 7
	v_cvt_pk_bf16_f32 v70, v64, v65
	v_cvt_pk_bf16_f32 v71, v66, v67
	s_nop 1
	v_mfma_f32_16x16x16_bf16 v[64:67], v[194:195], v[70:71], v[64:67]
	s_nop 7
	v_cvt_pk_bf16_f32 v70, v64, v65
	v_cvt_pk_bf16_f32 v71, v66, v67
	s_nop 1
	v_mfma_f32_16x16x16_bf16 v[64:67], v[68:69], v[70:71], v[64:67]

; __device__ __forceinline__ float b2f(u16 b) { return __uint_as_float(((unsigned)b) << 16); }
; __device__ __forceinline__ void scan_pc(const Params& p, int j, const u16* R, const u16* K, const u16* V, u16* Y, u16* YB) {
;     ...
;     auto load_yold = [&](int c) {
;       _Pragma("unroll") for (int jj = 0; jj < 4; ++jj) yo[jj] = b2f(ldo<u16>(Yw, (unsigned)(offK0[jj] + c * dK)));
;     };
;     ...
;         if (c + 1 < nch) { stage_b(c + 1); if (ymode == 1) load_yold(c + 1); }
.LBB0_2736:
	s_or_b64 exec, exec, s[30:31]
	s_andn2_b64 vcc, exec, s[20:21]
	s_cbranch_vccnz .LBB0_2738
	v_add_u32_e32 v64, s74, v174
	v_add_u32_e32 v65, s74, v173
	v_add_u32_e32 v66, s74, v172
	v_add_u32_e32 v67, s74, v171
	global_load_ushort v230, v64, s[66:67]
	s_nop 0
	global_load_ushort v231, v67, s[66:67]
	s_nop 0
	global_load_ushort v232, v65, s[66:67]
	s_nop 0
	global_load_ushort v233, v66, s[66:67]

; __device__ __forceinline__ float b2f(u16 b) { return __uint_as_float(((unsigned)b) << 16); }
; __device__ __forceinline__ float sigmoidf_(float x) { return __builtin_amdgcn_rcpf(1.f + __builtin_amdgcn_exp2f(-1.4426950408889634f * x)); }
; #define MFMA16(a, b, c) __builtin_amdgcn_mfma_f32_16x16x32_bf16(a, b, c, 0, 0, 0)
; #define MFMA4(a, b, c) __builtin_amdgcn_mfma_f32_16x16x16bf16_1k(a, b, c, 0, 0, 0)
; __device__ __forceinline__ void scan_pc(const Params& p, int j, const u16* R, const u16* K, const u16* V, u16* Y, u16* YB) {
;     ...
;     auto stage_a = [&](int c, const Raw& q_) {
;       u16* IMG = shm + (c % 3) * IMG_ELEMS;
;       f32x4 cw = {0.f, 0.f, 0.f, 0.f}, ca = {0.f, 0.f, 0.f, 0.f};
;       _Pragma("unroll") for (int ks = 0; ks < 2; ++ks) { cw = MFMA16(q_.rw[ks], LB[ks * 64], cw); ca = MFMA16(q_.ra[ks], LB[(2 + ks) * 64], ca); }
;       float kv[4], kk[4], ic[4], lw[4];
;       _Pragma("unroll") for (int jj = 0; jj < 4; ++jj) {
;         kv[jj] = b2f(q_.rk[jj]);
;         kk[jj] = kv[jj] * kkme;
;         float ss = row_sum(kk[jj] * kk[jj]);
;         reinterpret_cast<float*>(IMG + IMG_PL)[128 + w4 * 16 + fq * 4 + jj] = ss;
;         lw[jj] = -0.8750360036f * sigmoidf_(w0c + cw[jj]);
;         ic[jj] = sigmoidf_(a0c + ca[jj]);
;       }
;       s4 lhi = pack4(lw[0], lw[1], lw[2], lw[3]);
;       s4 llo = pack4(lw[0] - b2f((u16)lhi[0]), lw[1] - b2f((u16)lhi[1]), lw[2] - b2f((u16)lhi[2]), lw[3] - b2f((u16)lhi[3]));
;       f32x4 cum = {0.f, 0.f, 0.f, 0.f};
;       cum = MFMA4(ltri, lhi, cum);
;       cum = MFMA4(ltri, llo, cum);
;       float bt[4], kt[4], ep3 = 0.f;
;       _Pragma("unroll") for (int jj = 0; jj < 4; ++jj) {
;         float ep = __builtin_amdgcn_exp2f(cum[jj]), em = __builtin_amdgcn_exp2f(-cum[jj]), ex = __builtin_amdgcn_exp2f(cum[jj] - lw[jj]);
;         float at = -kk[jj] * ex;
;         float rraw = b2f(q_.rr[jj]);
;         float rt = rraw * ep;
;         float kd = kv[jj] * (1.f + (ic[jj] - 1.f) * kac);
;         bt[jj] = kk[jj] * ic[jj] * em;
;         kt[jj] = kd * em;
;         int t = fq * 4 + jj, kc = w4 * 16 + fr;
;         float bsum = row_sum(rraw * kd * rkc);
.LBB0_2739:
	s_or_saveexec_b64 s[26:27], s[26:27]
	s_mul_hi_u32 s30, s3, 0xaaaaaaab
	s_lshr_b32 s30, s30, 1
	s_mul_i32 s30, s30, 3
	s_sub_i32 s76, 2, s30
	v_add_u32_e32 v94, 2, v90
	s_xor_b64 exec, exec, s[26:27]
	s_cbranch_execz .LBB0_2745
	v_add_u32_e32 v50, 2, v90
	v_cmp_gt_u32_e32 vcc, s2, v50
	s_and_saveexec_b64 s[30:31], vcc
	s_cbranch_execz .LBB0_2744
	ds_read_b128 v[58:61], v111
	ds_read_b128 v[234:237], v111 offset:2048
	ds_read_b128 v[238:241], v111 offset:1024
	ds_read_b128 v[242:245], v111 offset:3072
	s_mov_b32 s62, 0xbf60025c
	v_add_u32_e32 v50, s76, v90
	s_waitcnt vmcnt(16) lgkmcnt(3)
	v_mfma_f32_16x16x32_bf16 v[20:23], v[20:23], v[58:61], 0
	s_waitcnt lgkmcnt(2)
	v_mfma_f32_16x16x32_bf16 v[28:31], v[28:31], v[234:237], 0
	s_waitcnt lgkmcnt(1)
	v_mfma_f32_16x16x32_bf16 v[16:19], v[16:19], v[238:241], v[20:23]
	s_waitcnt lgkmcnt(0)
	v_mfma_f32_16x16x32_bf16 v[20:23], v[24:27], v[242:245], v[28:31]
	v_lshl_or_b32 v161, v207, 16, v206
	v_lshl_or_b32 v159, v209, 16, v208
	v_lshl_or_b32 v160, v211, 16, v210
	v_lshl_or_b32 v158, v213, 16, v212
	v_lshl_or_b32 v82, v215, 16, v214
	v_lshl_or_b32 v83, v217, 16, v216
	s_nop 1
	v_add_f32_e32 v16, v152, v16
	v_add_f32_e32 v17, v152, v17
	v_mul_f32_e32 v16, 0xbfb8aa3b, v16
	s_nop 2
	v_add_f32_e32 v20, v153, v20
	v_mul_f32_e32 v20, 0xbfb8aa3b, v20
	v_exp_f32_e32 v20, v20
	v_mul_f32_e32 v17, 0xbfb8aa3b, v17
	v_add_f32_e32 v18, v152, v18
	v_add_f32_e32 v19, v152, v19
	v_add_f32_e32 v20, 1.0, v20
	v_rcp_f32_e32 v26, v20
	v_add_f32_e32 v20, v153, v21
	v_mul_f32_e32 v20, 0xbfb8aa3b, v20
	v_exp_f32_e32 v20, v20
	v_exp_f32_e32 v16, v16
	v_exp_f32_e32 v17, v17
	v_mul_f32_e32 v18, 0xbfb8aa3b, v18
	v_add_f32_e32 v20, 1.0, v20
	v_rcp_f32_e32 v27, v20
	v_add_f32_e32 v20, v153, v22
	v_mul_f32_e32 v20, 0xbfb8aa3b, v20
	v_exp_f32_e32 v20, v20
	v_mul_f32_e32 v19, 0xbfb8aa3b, v19
	v_exp_f32_e32 v18, v18
	v_exp_f32_e32 v19, v19
	v_add_f32_e32 v20, 1.0, v20
	v_rcp_f32_e32 v22, v20
	v_add_f32_e32 v20, v153, v23
	v_add_f32_e32 v16, 1.0, v16
	v_add_f32_e32 v17, 1.0, v17
	v_mul_f32_e32 v20, 0xbfb8aa3b, v20
	v_rcp_f32_e32 v16, v16
	v_rcp_f32_e32 v17, v17
	v_add_f32_e32 v18, 1.0, v18
	v_add_f32_e32 v19, 1.0, v19
	v_exp_f32_e32 v20, v20
	v_rcp_f32_e32 v18, v18
	v_rcp_f32_e32 v19, v19
	v_pk_mul_f32 v[28:29], v[16:17], s[62:63] op_sel_hi:[1,0]
	v_add_f32_e32 v20, 1.0, v20
	v_rcp_f32_e32 v23, v20
	v_pk_mul_f32 v[30:31], v[18:19], s[62:63] op_sel_hi:[1,0]
	v_cvt_pk_bf16_f32 v20, v28, v29
	v_mad_u32_u24 v24, v50, s80, 0
	v_cvt_pk_bf16_f32 v21, v30, v31
	v_and_b32_e32 v51, 0xffff0000, v20
	v_lshlrev_b32_e32 v50, 16, v20
	v_pk_fma_f32 v[16:17], v[16:17], s[62:63], v[50:51] op_sel_hi:[1,0,1] neg_lo:[0,0,1] neg_hi:[0,0,1]
	v_and_b32_e32 v51, 0xffff0000, v21
	v_lshlrev_b32_e32 v50, 16, v21
	v_pk_fma_f32 v[18:19], v[18:19], s[62:63], v[50:51] op_sel_hi:[1,0,1] neg_lo:[0,0,1] neg_hi:[0,0,1]
	v_cvt_pk_bf16_f32 v50, v16, v17
	v_cvt_pk_bf16_f32 v51, v18, v19
	v_mfma_f32_16x16x16_bf16 v[16:19], v[72:73], v[20:21], 0
	v_add_u32_e32 v60, v24, v115
	v_add_u32_e32 v61, v60, v117
	v_add3_u32 v66, v24, v117, v115
	v_mfma_f32_16x16x16_bf16 v[18:21], v[72:73], v[50:51], v[16:19]
	v_add_u32_e32 v25, v24, v113
	v_add_u32_e32 v62, v25, v112
	v_lshl_add_u32 v63, v97, 2, v25
	s_nop 4
	v_sub_f32_e32 v16, v18, v28
	v_exp_f32_e32 v58, v18
	v_exp_f32_e64 v50, -v18
	v_exp_f32_e32 v59, v16
	v_exp_f32_e32 v67, v19
	v_exp_f32_e64 v51, -v19
	v_sub_f32_e32 v16, v19, v29
	v_and_b32_e32 v19, 0xffff0000, v161
	v_lshlrev_b32_e32 v18, 16, v161
	v_pk_mul_f32 v[54:55], v[76:77], v[18:19]
	v_exp_f32_e32 v68, v16
	v_pk_mul_f32 v[16:17], v[54:55], v[54:55]
	s_nop 1
	v_mov_b32_dpp v16, v16 quad_perm:[1,0,3,2] row_mask:0xf bank_mask:0xf bound_ctrl:1
	v_mov_b32_dpp v17, v17 quad_perm:[1,0,3,2] row_mask:0xf bank_mask:0xf bound_ctrl:1
	v_pk_fma_f32 v[16:17], v[54:55], v[54:55], v[16:17]
	s_nop 1
	v_mov_b32_dpp v28, v16 quad_perm:[2,3,0,1] row_mask:0xf bank_mask:0xf bound_ctrl:1
	v_mov_b32_dpp v29, v17 quad_perm:[2,3,0,1] row_mask:0xf bank_mask:0xf bound_ctrl:1
	v_pk_add_f32 v[16:17], v[16:17], v[28:29]
	s_nop 1
	v_mov_b32_dpp v28, v16 row_half_mirror row_mask:0xf bank_mask:0xf bound_ctrl:1
	v_mov_b32_dpp v29, v17 row_half_mirror row_mask:0xf bank_mask:0xf bound_ctrl:1
	v_pk_add_f32 v[16:17], v[16:17], v[28:29]
	s_nop 1
	v_mov_b32_dpp v28, v16 row_ror:8 row_mask:0xf bank_mask:0xf bound_ctrl:1
	v_mov_b32_dpp v29, v17 row_ror:8 row_mask:0xf bank_mask:0xf bound_ctrl:1
	v_pk_add_f32 v[28:29], v[16:17], v[28:29]
	v_mul_f32_e64 v16, v59, -v54
	v_cvt_pk_bf16_f32 v16, v16, s0
	ds_write_b16 v61, v16
	v_pk_mul_f32 v[16:17], v[54:55], v[26:27]
	v_pk_add_f32 v[26:27], v[26:27], -1.0 op_sel_hi:[1,0]
	v_pk_mul_f32 v[16:17], v[16:17], v[50:51]
	v_pk_fma_f32 v[26:27], v[74:75], v[26:27], 1.0 op_sel_hi:[1,1,0]
	v_cvt_pk_bf16_f32 v54, v16, s0
	v_pk_mul_f32 v[26:27], v[26:27], v[18:19]
	ds_write_b16 v66, v54 offset:4608
	v_pk_mul_f32 v[18:19], v[26:27], v[50:51]
	v_mul_f32_e64 v54, v68, -v55
	v_cvt_pk_bf16_f32 v50, v18, s0
	ds_write_b16 v66, v50 offset:6912
	v_lshlrev_b32_e32 v50, 16, v160
	v_and_b32_e32 v51, 0xffff0000, v160
; __device__ __forceinline__ float b2f(u16 b) { return __uint_as_float(((unsigned)b) << 16); }
; __device__ __forceinline__ void scan_pc(const Params& p, int j, const u16* R, const u16* K, const u16* V, u16* Y, u16* YB) {
;     ...
;       _Pragma("unroll") for (int jj = 0; jj < 4; ++jj) {
;         float ep = __builtin_amdgcn_exp2f(cum[jj]), em = __builtin_amdgcn_exp2f(-cum[jj]), ex = __builtin_amdgcn_exp2f(cum[jj] - lw[jj]);
;         float at = -kk[jj] * ex;
;         float rraw = b2f(q_.rr[jj]);
;         float rt = rraw * ep;
;         float kd = kv[jj] * (1.f + (ic[jj] - 1.f) * kac);
;         bt[jj] = kk[jj] * ic[jj] * em;
;         kt[jj] = kd * em;
;         int t = fq * 4 + jj, kc = w4 * 16 + fr;
;         float bsum = row_sum(rraw * kd * rkc);
;         reinterpret_cast<float*>(IMG + IMG_PL)[64 + w4 * 16 + t] = bsum;
;         IMG[(0 * 16 + t) * XT_LD + kc] = f2b(at);
;         IMG[(1 * 16 + t) * XT_LD + kc] = f2b(rt);
;         IMG[(2 * 16 + t) * XT_LD + kc] = f2b(bt[jj]);
;         IMG[(3 * 16 + t) * XT_LD + kc] = f2b(kt[jj]);
;         if (jj == 3) ep3 = ep;
;       }
;       if (fq == 3) reinterpret_cast<float*>(IMG + IMG_PL)[w4 * 16 + fr] = ep3;
;       *reinterpret_cast<s4*>(IMG + IMG_XK + (0 * 64 + w4 * 16 + fr) * XK_LD + fq * 4) = pack4(bt[0], bt[1], bt[2], bt[3]);
;       *reinterpret_cast<s4*>(IMG + IMG_XK + (1 * 64 + w4 * 16 + fr) * XK_LD + fq * 4) = pack4(kt[0], kt[1], kt[2], kt[3]);
;       s4 vp; _Pragma("unroll") for (int jj = 0; jj < 4; ++jj) vp[jj] = (short)q_.rv[jj];
;       *reinterpret_cast<s4*>(IMG + IMG_VT + (w4 * 16 + fr) * XK_LD + fq * 4) = vp;
	v_mul_f32_e32 v55, v58, v50
	v_cvt_pk_bf16_f32 v55, v55, s0
	v_pk_mul_f32 v[26:27], v[26:27], v[50:51]
	ds_write_b16 v66, v55 offset:2304
	v_mul_f32_e32 v55, v67, v51
	v_pk_mul_f32 v[50:51], v[78:79], v[26:27]
	v_exp_f32_e32 v66, v20
	s_nop 0
	v_mov_b32_dpp v50, v50 quad_perm:[1,0,3,2] row_mask:0xf bank_mask:0xf bound_ctrl:1
	v_mov_b32_dpp v51, v51 quad_perm:[1,0,3,2] row_mask:0xf bank_mask:0xf bound_ctrl:1
	v_pk_fma_f32 v[26:27], v[78:79], v[26:27], v[50:51]
	s_nop 1
	v_mov_b32_dpp v50, v26 quad_perm:[2,3,0,1] row_mask:0xf bank_mask:0xf bound_ctrl:1
	v_mov_b32_dpp v51, v27 quad_perm:[2,3,0,1] row_mask:0xf bank_mask:0xf bound_ctrl:1
	v_pk_add_f32 v[26:27], v[26:27], v[50:51]
	s_nop 1
	v_mov_b32_dpp v50, v26 row_half_mirror row_mask:0xf bank_mask:0xf bound_ctrl:1
	v_mov_b32_dpp v51, v27 row_half_mirror row_mask:0xf bank_mask:0xf bound_ctrl:1
	v_pk_add_f32 v[26:27], v[26:27], v[50:51]
	s_nop 1
	v_mov_b32_dpp v50, v26 row_ror:8 row_mask:0xf bank_mask:0xf bound_ctrl:1
	v_mov_b32_dpp v51, v27 row_ror:8 row_mask:0xf bank_mask:0xf bound_ctrl:1
	v_pk_add_f32 v[58:59], v[26:27], v[50:51]
	v_cvt_pk_bf16_f32 v26, v54, s0
	v_add_u32_e32 v27, v60, v120
	ds_write_b16 v27, v26
	v_cvt_pk_bf16_f32 v26, v55, s0
	v_add3_u32 v27, v24, v120, v115
	ds_write_b16 v27, v26 offset:2304
	v_cvt_pk_bf16_f32 v26, v17, s0
	v_exp_f32_e64 v50, -v20
	v_sub_f32_e32 v20, v20, v30
	v_and_b32_e32 v55, 0xffff0000, v159
	v_lshlrev_b32_e32 v54, 16, v159
	ds_write_b16 v27, v26 offset:4608
	v_cvt_pk_bf16_f32 v26, v19, s0
	v_exp_f32_e32 v67, v20
	v_sub_f32_e32 v20, v21, v31
	v_pk_mul_f32 v[60:61], v[76:77], v[54:55]
	ds_write_b16 v27, v26 offset:6912
	v_exp_f32_e32 v26, v21
	v_exp_f32_e64 v51, -v21
	v_exp_f32_e32 v68, v20
	v_pk_mul_f32 v[20:21], v[60:61], v[60:61]
	s_nop 1
	v_mov_b32_dpp v20, v20 quad_perm:[1,0,3,2] row_mask:0xf bank_mask:0xf bound_ctrl:1
	v_mov_b32_dpp v21, v21 quad_perm:[1,0,3,2] row_mask:0xf bank_mask:0xf bound_ctrl:1
	v_pk_fma_f32 v[20:21], v[60:61], v[60:61], v[20:21]
	s_nop 1
	v_mov_b32_dpp v30, v20 quad_perm:[2,3,0,1] row_mask:0xf bank_mask:0xf bound_ctrl:1
	v_mov_b32_dpp v31, v21 quad_perm:[2,3,0,1] row_mask:0xf bank_mask:0xf bound_ctrl:1
	v_pk_add_f32 v[20:21], v[20:21], v[30:31]
	s_nop 1
	v_mov_b32_dpp v30, v20 row_half_mirror row_mask:0xf bank_mask:0xf bound_ctrl:1
	v_mov_b32_dpp v31, v21 row_half_mirror row_mask:0xf bank_mask:0xf bound_ctrl:1
	v_pk_add_f32 v[20:21], v[20:21], v[30:31]
	s_nop 1
	v_mov_b32_dpp v30, v20 row_ror:8 row_mask:0xf bank_mask:0xf bound_ctrl:1
	v_mov_b32_dpp v31, v21 row_ror:8 row_mask:0xf bank_mask:0xf bound_ctrl:1
	v_pk_add_f32 v[30:31], v[20:21], v[30:31]
	v_mul_f32_e64 v20, v67, -v60
	v_cvt_pk_bf16_f32 v20, v20, s0
	ds_write_b16 v27, v20 offset:144
	v_pk_mul_f32 v[20:21], v[60:61], v[22:23]
	v_pk_add_f32 v[22:23], v[22:23], -1.0 op_sel_hi:[1,0]
	v_pk_mul_f32 v[20:21], v[20:21], v[50:51]
	ds_write_b128 v62, v[28:31] offset:17408
	v_cvt_pk_bf16_f32 v28, v20, s0
	v_pk_fma_f32 v[22:23], v[74:75], v[22:23], 1.0 op_sel_hi:[1,1,0]
	ds_write_b16 v27, v28 offset:4752
	v_pk_mul_f32 v[28:29], v[22:23], v[54:55]
	v_and_b32_e32 v31, 0xffff0000, v158
	v_pk_mul_f32 v[22:23], v[28:29], v[50:51]
	v_mul_f32_e64 v62, v68, -v61
	v_cvt_pk_bf16_f32 v30, v22, s0
	ds_write_b16 v27, v30 offset:7056
	v_lshlrev_b32_e32 v30, 16, v158
	v_mul_f32_e32 v50, v66, v30
	v_cvt_pk_bf16_f32 v50, v50, s0
	v_pk_mul_f32 v[28:29], v[28:29], v[30:31]
	ds_write_b16 v27, v50 offset:2448
	v_mul_f32_e32 v50, v26, v31
	v_pk_mul_f32 v[30:31], v[78:79], v[28:29]
	s_nop 1
	v_mov_b32_dpp v30, v30 quad_perm:[1,0,3,2] row_mask:0xf bank_mask:0xf bound_ctrl:1
	v_mov_b32_dpp v31, v31 quad_perm:[1,0,3,2] row_mask:0xf bank_mask:0xf bound_ctrl:1
	v_pk_fma_f32 v[28:29], v[78:79], v[28:29], v[30:31]
	s_nop 1
	v_mov_b32_dpp v30, v28 quad_perm:[2,3,0,1] row_mask:0xf bank_mask:0xf bound_ctrl:1
	v_mov_b32_dpp v31, v29 quad_perm:[2,3,0,1] row_mask:0xf bank_mask:0xf bound_ctrl:1
	v_pk_add_f32 v[28:29], v[28:29], v[30:31]
	s_nop 1
	v_mov_b32_dpp v30, v28 row_half_mirror row_mask:0xf bank_mask:0xf bound_ctrl:1
	v_mov_b32_dpp v31, v29 row_half_mirror row_mask:0xf bank_mask:0xf bound_ctrl:1
	v_pk_add_f32 v[28:29], v[28:29], v[30:31]
	s_nop 1
	v_mov_b32_dpp v30, v28 row_ror:8 row_mask:0xf bank_mask:0xf bound_ctrl:1
	v_mov_b32_dpp v31, v29 row_ror:8 row_mask:0xf bank_mask:0xf bound_ctrl:1
	v_pk_add_f32 v[60:61], v[28:29], v[30:31]
	v_cvt_pk_bf16_f32 v28, v62, s0
	ds_write_b16 v27, v28 offset:288
	v_cvt_pk_bf16_f32 v28, v50, s0
	ds_write_b16 v27, v28 offset:2592
	v_cvt_pk_bf16_f32 v28, v21, s0
	ds_write_b16 v27, v28 offset:4896
	v_cvt_pk_bf16_f32 v28, v23, s0
	ds_write_b128 v63, v[58:61] offset:17152
	ds_write_b16 v27, v28 offset:7200
	s_and_saveexec_b64 s[62:63], s[12:13]
	v_lshl_add_u32 v25, v96, 2, v25
	ds_write_b32 v25, v26 offset:16896
	s_or_b64 exec, exec, s[62:63]
	v_cvt_pk_bf16_f32 v16, v16, v17
	v_cvt_pk_bf16_f32 v17, v20, v21
	v_add3_u32 v20, v24, v127, v133
	v_cvt_pk_bf16_f32 v18, v18, v19
	v_cvt_pk_bf16_f32 v19, v22, v23
	ds_write2st64_b64 v20, v[16:17], v[18:19] offset0:18 offset1:23
	ds_write_b64 v20, v[82:83] offset:14336

; __device__ __forceinline__ float b2f(u16 b) { return __uint_as_float(((unsigned)b) << 16); }
; #define MFMA4(a, b, c) __builtin_amdgcn_mfma_f32_16x16x16bf16_1k(a, b, c, 0, 0, 0)
; __device__ __forceinline__ s4 pack4v(f32x4 v) { return pack4(v[0], v[1], v[2], v[3]); }
; __device__ __forceinline__ void scan_pc(const Params& p, int j, const u16* R, const u16* K, const u16* V, u16* Y, u16* YB) {
;     ...
;       _Pragma("unroll") for (int jj = 0; jj < 4; ++jj) yo[jj] = b2f(ldo<u16>(Yw, (unsigned)(offK0[jj] + c * dK)));
;     ...
;       const u16* IMG = shm + (c % 3) * IMG_ELEMS;
;       const u16* MM = shm + 4 * IMG_ELEMS + (c & 1) * MM_ELEMS;
;       s4 vb = *reinterpret_cast<const s4*>(IMG + IMG_VT + (w4 * 16 + fr) * XK_LD + fq * 4);
;       f32x4 z4 = {0.f, 0.f, 0.f, 0.f};
;       const float* PL = reinterpret_cast<const float*>(IMG + IMG_PL);
;       float4 iv = *reinterpret_cast<const float4*>(PL + 192 + fq * 4);
;       f32x4 rhs = z4;
;       f32x4 y = MFMA4(*reinterpret_cast<const s4*>(MM + (3 * 16 + fr) * XK_LD + fq * 4), vb, z4);
;       _Pragma("unroll") for (int kb = 0; kb < 4; ++kb) {
;         rhs = MFMA4(*reinterpret_cast<const s4*>(IMG + (0 * 16 + fr) * XT_LD + kb * 16 + fq * 4), Zb[kb], rhs);
;         y = MFMA4(*reinterpret_cast<const s4*>(IMG + (1 * 16 + fr) * XT_LD + kb * 16 + fq * 4), Zb[kb], y);
;       }
;       rhs[0] *= iv.x; rhs[1] *= iv.y; rhs[2] *= iv.z; rhs[3] *= iv.w;
;       rhs = MFMA4(*reinterpret_cast<const s4*>(MM + (1 * 16 + fr) * XK_LD + fq * 4), vb, rhs);
;       f32x4 u = MFMA4(*reinterpret_cast<const s4*>(MM + (0 * 16 + fr) * XK_LD + fq * 4), pack4v(rhs), z4);
;       y = MFMA4(*reinterpret_cast<const s4*>(MM + (2 * 16 + fr) * XK_LD + fq * 4), pack4v(u), y);
;       s4 ub = pack4(u[0] * iv.x, u[1] * iv.y, u[2] * iv.z, u[3] * iv.w);
;       _Pragma("unroll") for (int kb = 0; kb < 4; ++kb) {
;         Z[kb] = MFMA4(*reinterpret_cast<const s4*>(IMG + IMG_XK + (0 * 64 + kb * 16 + fr) * XK_LD + fq * 4), ub, Z[kb]);
;         Z[kb] = MFMA4(*reinterpret_cast<const s4*>(IMG + IMG_XK + (1 * 64 + kb * 16 + fr) * XK_LD + fq * 4), vb, Z[kb]);
;         float4 pl = *reinterpret_cast<const float4*>(PL + kb * 16 + fq * 4);
;         Z[kb][0] *= pl.x; Z[kb][1] *= pl.y; Z[kb][2] *= pl.z; Z[kb][3] *= pl.w;
;         Zb[kb] = pack4v(Z[kb]);
;       }
.LBB0_2745:
	s_or_b64 exec, exec, s[26:27]
	s_waitcnt lgkmcnt(0)
	s_barrier
	s_and_saveexec_b64 s[26:27], s[10:11]
	s_xor_b64 s[26:27], exec, s[26:27]
	s_cbranch_execz .LBB0_2764
	v_add_u32_e32 v50, s75, v90
	v_mad_u32_u24 v91, v50, s80, 0
	v_add3_u32 v51, v91, v146, v179
	ds_read2_b64 v[66:69], v147 offset0:160 offset1:240
	ds_read2_b64 v[92:95], v51 offset1:4
	v_add3_u32 v50, v91, v127, v179
	ds_read_b64 v[180:181], v50 offset:14336
	v_lshl_add_u32 v50, v97, 2, v91
	ds_read_b128 v[58:61], v50 offset:17664
	v_add_u32_e32 v50, 0x800, v51
	ds_read2_b64 v[198:201], v50 offset0:32 offset1:36
	s_waitcnt lgkmcnt(2)
	v_mfma_f32_16x16x16_bf16 v[68:71], v[68:69], v[180:181], 0
	v_add3_u32 v193, v91, v144, v133
	v_add_u32_e32 v202, 0x2c00, v193
	v_add_u32_e32 v91, v91, v112
	v_mfma_f32_16x16x16_bf16 v[194:197], v[92:93], v[64:65], 0
	v_readlane_b32 s80, v247, 14
	v_readlane_b32 s81, v247, 15
	v_readlane_b32 s82, v247, 16
	s_waitcnt lgkmcnt(0)
	v_mfma_f32_16x16x16_bf16 v[62:65], v[198:199], v[64:65], v[68:71]
	v_readlane_b32 s83, v247, 17
	s_mov_b32 s81, s80
	s_mov_b32 s82, s80
	v_mfma_f32_16x16x16_bf16 v[68:71], v[94:95], v[56:57], v[194:197]
	ds_read2_b64 v[92:95], v51 offset0:8 offset1:12
	v_add_u32_e32 v51, 0x2000, v193
	s_mov_b32 s83, s80
	s_waitcnt lgkmcnt(0)
	v_mfma_f32_16x16x16_bf16 v[68:71], v[92:93], v[52:53], v[68:71]
	ds_read2_b64 v[194:197], v147 offset1:80
	v_writelane_b32 v247, s80, 14
	v_mfma_f32_16x16x16_bf16 v[68:71], v[94:95], v[48:49], v[68:71]
	ds_read2_b64 v[92:95], v50 offset0:40 offset1:44
	v_writelane_b32 v247, s81, 15
	v_writelane_b32 v247, s82, 16
	v_mfma_f32_16x16x16_bf16 v[198:201], v[200:201], v[56:57], v[62:65]
	v_writelane_b32 v247, s83, 17
	s_nop 2
	v_pk_mul_f32 v[56:57], v[60:61], v[70:71]
	v_pk_mul_f32 v[54:55], v[58:59], v[68:69]
	ds_read2_b64 v[62:65], v51 offset0:128 offset1:208
	ds_read2_b64 v[68:71], v202 offset0:64 offset1:144
	s_waitcnt lgkmcnt(3)
	v_mfma_f32_16x16x16_bf16 v[54:57], v[196:197], v[180:181], v[54:57]
	s_movk_i32 s80, 0x4540
	s_nop 6
	v_cvt_pk_bf16_f32 v50, v54, v55
	v_cvt_pk_bf16_f32 v51, v56, v57
	s_nop 1
	v_mfma_f32_16x16x16_bf16 v[54:57], v[194:195], v[50:51], 0
	s_nop 7
	v_pk_mul_f32 v[50:51], v[58:59], v[54:55]
	v_pk_mul_f32 v[58:59], v[60:61], v[56:57]
	v_cvt_pk_bf16_f32 v202, v50, v51
	s_waitcnt lgkmcnt(2)
	v_mfma_f32_16x16x16_bf16 v[50:53], v[92:93], v[52:53], v[198:201]
	v_cvt_pk_bf16_f32 v203, v58, v59
	v_cvt_pk_bf16_f32 v204, v54, v55
	v_add_u32_e32 v54, 0x2800, v193
	s_waitcnt lgkmcnt(1)
	v_mfma_f32_16x16x16_bf16 v[40:43], v[62:63], v[202:203], v[40:43]
	v_cvt_pk_bf16_f32 v205, v56, v57
	ds_read_b128 v[60:63], v91 offset:16896
	ds_read_b128 v[56:59], v91 offset:16960
	ds_read2_b64 v[194:197], v54 offset0:32 offset1:112
	v_mfma_f32_16x16x16_bf16 v[92:95], v[94:95], v[48:49], v[50:53]
	v_add_u32_e32 v54, 0x3000, v193
	ds_read2_b64 v[198:201], v54 offset0:96 offset1:176
	s_nop 0
	ds_read_b128 v[52:55], v91 offset:17024
	ds_read_b128 v[48:51], v91 offset:17088
	v_add_u32_e32 v91, s74, v174
	s_waitcnt lgkmcnt(6)
	v_mfma_f32_16x16x16_bf16 v[40:43], v[68:69], v[180:181], v[40:43]
	v_mfma_f32_16x16x16_bf16 v[66:69], v[66:67], v[204:205], v[92:95]
	v_mfma_f32_16x16x16_bf16 v[44:47], v[64:65], v[202:203], v[44:47]
	s_andn2_b64 vcc, exec, s[20:21]
	s_cbranch_vccnz .Lyold_done_b
	s_waitcnt vmcnt(0)
	v_lshlrev_b32_e32 v87, 16, v230
	v_lshlrev_b32_e32 v88, 16, v231
	v_lshlrev_b32_e32 v86, 16, v232
	v_lshlrev_b32_e32 v89, 16, v233
; #define MFMA4(a, b, c) __builtin_amdgcn_mfma_f32_16x16x16bf16_1k(a, b, c, 0, 0, 0)
; __device__ __forceinline__ void scan_pc(const Params& p, int j, const u16* R, const u16* K, const u16* V, u16* Y, u16* YB) {
;     ...
;       u16* IMG = shm + (c % 3) * IMG_ELEMS;
;       u16* MM = shm + 4 * IMG_ELEMS + (c & 1) * MM_ELEMS;
;       int ai = (w4 < 2) ? 0 : 1, bi = (w4 & 1) ? 3 : 2;
;       f32x4 mt = {0.f, 0.f, 0.f, 0.f}, nc = {0.f, 0.f, 0.f, 0.f};
;       _Pragma("unroll") for (int kb = 0; kb < 4; ++kb) {
;         s4 xa = *reinterpret_cast<const s4*>(IMG + (ai * 16 + fr) * XT_LD + kb * 16 + fq * 4);
;         s4 xb = *reinterpret_cast<const s4*>(IMG + (bi * 16 + fr) * XT_LD + kb * 16 + fq * 4);
;         mt = MFMA4(xb, xa, mt);
;         if (w4 == 0) nc = MFMA4(xa, xb, nc);
;       }
;       float* SSQ = reinterpret_cast<float*>(IMG + IMG_PL) + 128;
;       float inv_t = rsqrtf(fmaxf((SSQ[fr] + SSQ[16 + fr]) + (SSQ[32 + fr] + SSQ[48 + fr]), 1e-24f));
;       if (w4 == 3) SSQ[64 + fr] = inv_t;
;       float ivr = (w4 < 2) ? inv_t : 1.f;
;       float sc_[4];
;       _Pragma("unroll") for (int jj = 0; jj < 4; ++jj) {
;         float ivj = __builtin_bit_cast(float, __builtin_amdgcn_ds_bpermute(((lane & 48) | (fq * 4 + jj)) << 2, __builtin_bit_cast(int, inv_t)));
;         sc_[jj] = ivr * (((w4 & 1) == 0) ? ivj : 1.f);
;         mt[jj] *= sc_[jj] * keepm[jj];
;       }
;       if (w4 == 0) {
;         _Pragma("unroll") for (int jj = 0; jj < 4; ++jj) nc[jj] *= sc_[jj] * keepn[jj];
;         f32x4 z4 = {0.f, 0.f, 0.f, 0.f};
;         s4 pN = pack4v(nc), pNT = pack4v(mt);
;         f32x4 n2 = MFMA4(pNT, pN, z4);
;         f32x4 n2t = MFMA4(pN, pNT, z4);
;         s4 pN2 = pack4v(n2), pN2T = pack4v(n2t);
;         f32x4 n4 = MFMA4(pN2T, pN2, z4);
;         f32x4 n4t = MFMA4(pN2, pN2T, z4);
;         s4 pN4 = pack4v(n4), pN4T = pack4v(n4t);
;         f32x4 n8 = MFMA4(pN4T, pN4, z4);
;         s4 pN8 = pack4v(n8);
;         f32x4 tt = mt;
;         _Pragma("unroll") for (int jj = 0; jj < 4; ++jj) tt[jj] += diagm[jj];
;         tt = MFMA4(pN2, pack4v(tt), tt);
;         tt = MFMA4(pN4, pack4v(tt), tt);
;         tt = MFMA4(pN8, pack4v(tt), tt);
;         mt = tt;
;     ...
;       _Pragma("unroll") for (int jj = 0; jj < 4; ++jj)
;         sto<u16>(Yw, (unsigned)(offK0[jj] + c * dK), f2b(ymode == 1 ? y[jj] + yo[jj] : y[jj]));
.Lyold_done_b:
	s_nop 1
	v_add_u32_e32 v94, 2, v90
	s_nop 3
	v_add_f32_e32 v92, v87, v66
	v_cndmask_b32_e64 v66, v66, v92, s[20:21]
	v_add_f32_e32 v65, v86, v67
	v_cvt_pk_bf16_f32 v64, v66, s0
	v_cndmask_b32_e64 v65, v67, v65, s[20:21]
	s_waitcnt lgkmcnt(3)
	v_mfma_f32_16x16x16_bf16 v[32:35], v[194:195], v[202:203], v[32:35]
	global_store_short v91, v64, s[70:71]
	v_add_u32_e32 v64, s74, v173
	v_cvt_pk_bf16_f32 v65, v65, s0
	v_mfma_f32_16x16x16_bf16 v[36:39], v[196:197], v[202:203], v[36:39]
	global_store_short v64, v65, s[70:71]
	v_add_f32_e32 v65, v89, v68
	v_cndmask_b32_e64 v65, v68, v65, s[20:21]
	v_mfma_f32_16x16x16_bf16 v[44:47], v[70:71], v[180:181], v[44:47]
	v_add_u32_e32 v64, s74, v172
	v_cvt_pk_bf16_f32 v65, v65, s0
	global_store_short v64, v65, s[70:71]
	s_waitcnt lgkmcnt(2)
	v_mfma_f32_16x16x16_bf16 v[32:35], v[198:199], v[180:181], v[32:35]
	v_add_f32_e32 v64, v88, v69
	v_cndmask_b32_e64 v64, v69, v64, s[20:21]
	v_add_u32_e32 v65, s74, v171
	v_mfma_f32_16x16x16_bf16 v[36:39], v[200:201], v[180:181], v[36:39]
	v_cvt_pk_bf16_f32 v64, v64, s0
	v_cmp_gt_u32_e32 vcc, s2, v94
	global_store_short v65, v64, s[70:71]
	s_and_saveexec_b64 s[62:63], vcc
	s_cbranch_execz .LBB0_2763
	v_add_u32_e32 v64, s76, v90
	v_mad_u32_u24 v95, v64, s80, 0
	v_add3_u32 v180, v95, v136, v179
	v_add3_u32 v179, v95, v134, v179
	ds_read_b64 v[90:91], v180
	ds_read_b64 v[92:93], v179
	ds_read_b64 v[206:207], v180 offset:32
	ds_read_b64 v[208:209], v179 offset:32
	ds_read_b64 v[210:211], v180 offset:64
	ds_read_b64 v[212:213], v179 offset:64
	ds_read_b64 v[214:215], v180 offset:96
	ds_read_b64 v[216:217], v179 offset:96
	v_lshl_add_u32 v218, v96, 2, v95
	v_add_u32_e32 v219, 0x4400, v218
	ds_read2_b32 v[220:221], v219 offset1:16
	ds_read2_b32 v[222:223], v219 offset0:32 offset1:48
	v_readlane_b32 s76, v247, 14
	v_readlane_b32 s77, v247, 15
	v_readlane_b32 s78, v247, 16
	v_readlane_b32 s79, v247, 17
	v_mov_b64_e32 v[68:69], s[76:77]
	s_waitcnt lgkmcnt(8)
	v_mfma_f32_16x16x16_bf16 v[64:67], v[90:91], v[92:93], 0
	v_mov_b64_e32 v[70:71], s[78:79]
	s_and_saveexec_b64 s[30:31], s[14:15]
	v_mfma_f32_16x16x16_bf16 v[68:71], v[92:93], v[90:91], 0
	s_or_b64 exec, exec, s[30:31]
	s_waitcnt lgkmcnt(6)
	v_mfma_f32_16x16x16_bf16 v[64:67], v[206:207], v[208:209], v[64:67]
	s_and_saveexec_b64 s[30:31], s[14:15]
	v_mfma_f32_16x16x16_bf16 v[68:71], v[208:209], v[206:207], v[68:71]
	s_or_b64 exec, exec, s[30:31]
	s_waitcnt lgkmcnt(4)
	v_mfma_f32_16x16x16_bf16 v[64:67], v[210:211], v[212:213], v[64:67]
	s_and_saveexec_b64 s[30:31], s[14:15]
	v_mfma_f32_16x16x16_bf16 v[68:71], v[212:213], v[210:211], v[68:71]
	s_or_b64 exec, exec, s[30:31]
	s_waitcnt lgkmcnt(2)
	v_mfma_f32_16x16x16_bf16 v[64:67], v[214:215], v[216:217], v[64:67]
	s_and_saveexec_b64 s[30:31], s[14:15]
	v_mfma_f32_16x16x16_bf16 v[68:71], v[216:217], v[214:215], v[68:71]
	s_or_b64 exec, exec, s[30:31]
	v_lshl_add_u32 v91, v96, 2, v95
	s_waitcnt lgkmcnt(0)
	v_add_f32_e32 v179, v220, v221
	v_add_f32_e32 v90, v222, v223
	v_add_f32_e32 v90, v179, v90
	v_max_f32_e32 v90, 0x179abe15, v90
	v_rsq_f32_e32 v90, v90
	s_and_saveexec_b64 s[30:31], s[16:17]
	ds_write_b32 v91, v90 offset:17664
	s_or_b64 exec, exec, s[30:31]
	ds_bpermute_b32 v91, v138, v90
	ds_bpermute_b32 v92, v139, v90
	v_cndmask_b32_e64 v93, 1.0, v90, s[6:7]
	ds_bpermute_b32 v179, v140, v90
	ds_bpermute_b32 v224, v141, v90
	s_waitcnt lgkmcnt(3)
	v_cndmask_b32_e64 v91, 1.0, v91, s[18:19]
	s_waitcnt lgkmcnt(2)
	v_cndmask_b32_e64 v92, 1.0, v92, s[18:19]
	v_mul_f32_e32 v91, v93, v91
	v_mul_f32_e32 v180, v98, v91
	v_mul_f32_e32 v92, v93, v92
	v_mul_f32_e32 v64, v64, v180
	v_mul_f32_e32 v180, v101, v92
	v_mul_f32_e32 v65, v65, v180
	s_waitcnt lgkmcnt(1)
	v_cndmask_b32_e64 v90, 1.0, v179, s[18:19]
	v_mul_f32_e32 v90, v93, v90
	v_mul_f32_e32 v179, v104, v90
	v_mul_f32_e32 v66, v66, v179
	s_waitcnt lgkmcnt(0)
	v_cndmask_b32_e64 v179, 1.0, v224, s[18:19]
	v_mul_f32_e32 v93, v93, v179
	v_mul_f32_e32 v179, v107, v93
	v_mul_f32_e32 v67, v67, v179
	s_and_saveexec_b64 s[30:31], s[14:15]
	s_cbranch_execz .LBB0_2759
	v_mul_f32_e32 v91, v99, v91
	v_mul_f32_e32 v90, v105, v90
	v_mul_f32_e32 v68, v68, v91
	v_mul_f32_e32 v91, v102, v92
	v_mul_f32_e32 v70, v70, v90
	v_mul_f32_e32 v90, v108, v93
	v_mul_f32_e32 v69, v69, v91
	v_mul_f32_e32 v71, v71, v90
	v_cvt_pk_bf16_f32 v90, v68, v69
	v_cvt_pk_bf16_f32 v91, v70, v71
	v_cvt_pk_bf16_f32 v92, v64, v65
	v_cvt_pk_bf16_f32 v93, v66, v67
	v_add_f32_e32 v64, v100, v64
	v_add_f32_e32 v65, v103, v65
	v_mfma_f32_16x16x16_bf16 v[68:71], v[92:93], v[90:91], 0
	v_add_f32_e32 v66, v106, v66
	v_add_f32_e32 v67, v109, v67
	v_mfma_f32_16x16x16_bf16 v[90:93], v[90:91], v[92:93], 0
	s_nop 4
	v_cvt_pk_bf16_f32 v180, v68, v69
	v_cvt_pk_bf16_f32 v181, v70, v71
	s_nop 0
	v_cvt_pk_bf16_f32 v90, v90, v91
	v_cvt_pk_bf16_f32 v91, v92, v93
	s_nop 1
	v_mfma_f32_16x16x16_bf16 v[68:71], v[90:91], v[180:181], 0
	v_mfma_f32_16x16x16_bf16 v[90:93], v[180:181], v[90:91], 0
	s_nop 6
	v_cvt_pk_bf16_f32 v194, v68, v69
	v_cvt_pk_bf16_f32 v195, v70, v71
	v_cvt_pk_bf16_f32 v68, v90, v91
	v_cvt_pk_bf16_f32 v69, v92, v93
	s_nop 1
	v_mfma_f32_16x16x16_bf16 v[68:71], v[68:69], v[194:195], 0
	s_nop 7
	v_cvt_pk_bf16_f32 v68, v68, v69
	v_cvt_pk_bf16_f32 v69, v70, v71
	v_cvt_pk_bf16_f32 v70, v64, v65
	v_cvt_pk_bf16_f32 v71, v66, v67
	s_nop 1
	v_mfma_f32_16x16x16_bf16 v[64:67], v[180:181], v[70:71], v[64:67]
	s_nop 7
	v_cvt_pk_bf16_f32 v70, v64, v65
	v_cvt_pk_bf16_f32 v71, v66, v67
	s_nop 1
	v_mfma_f32_16x16x16_bf16 v[64:67], v[194:195], v[70:71], v[64:67]
	s_nop 7
	v_cvt_pk_bf16_f32 v70, v64, v65
	v_cvt_pk_bf16_f32 v71, v66, v67
	s_nop 1
	v_mfma_f32_16x16x16_bf16 v[64:67], v[68:69], v[70:71], v[64:67]

; __device__ __forceinline__ float b2f(u16 b) { return __uint_as_float(((unsigned)b) << 16); }
; __device__ __forceinline__ void scan_pc(const Params& p, int j, const u16* R, const u16* K, const u16* V, u16* Y, u16* YB) {
;     ...
;     auto load_yold = [&](int c) {
;       _Pragma("unroll") for (int jj = 0; jj < 4; ++jj) yo[jj] = b2f(ldo<u16>(Yw, (unsigned)(offK0[jj] + c * dK)));
;     };
;     ...
;         if (c + 1 < nch) { stage_b(c + 1); if (ymode == 1) load_yold(c + 1); }
.LBB0_2761:
	s_or_b64 exec, exec, s[30:31]
	s_andn2_b64 vcc, exec, s[20:21]
	s_cbranch_vccnz .LBB0_2763
	v_add_u32_e32 v64, s74, v170
	v_add_u32_e32 v65, s74, v169
	v_add_u32_e32 v66, s74, v168
	v_add_u32_e32 v67, s74, v167
	global_load_ushort v230, v64, s[66:67]
	s_nop 0
	global_load_ushort v231, v67, s[66:67]
	s_nop 0
	global_load_ushort v232, v65, s[66:67]
	s_nop 0
	global_load_ushort v233, v66, s[66:67]

; __device__ __forceinline__ float b2f(u16 b) { return __uint_as_float(((unsigned)b) << 16); }
; __device__ __forceinline__ float sigmoidf_(float x) { return __builtin_amdgcn_rcpf(1.f + __builtin_amdgcn_exp2f(-1.4426950408889634f * x)); }
; #define MFMA16(a, b, c) __builtin_amdgcn_mfma_f32_16x16x32_bf16(a, b, c, 0, 0, 0)
; #define MFMA4(a, b, c) __builtin_amdgcn_mfma_f32_16x16x16bf16_1k(a, b, c, 0, 0, 0)
; __device__ __forceinline__ void scan_pc(const Params& p, int j, const u16* R, const u16* K, const u16* V, u16* Y, u16* YB) {
;     ...
;     auto stage_a = [&](int c, const Raw& q_) {
;       u16* IMG = shm + (c % 3) * IMG_ELEMS;
;       f32x4 cw = {0.f, 0.f, 0.f, 0.f}, ca = {0.f, 0.f, 0.f, 0.f};
;       _Pragma("unroll") for (int ks = 0; ks < 2; ++ks) { cw = MFMA16(q_.rw[ks], LB[ks * 64], cw); ca = MFMA16(q_.ra[ks], LB[(2 + ks) * 64], ca); }
;       float kv[4], kk[4], ic[4], lw[4];
;       _Pragma("unroll") for (int jj = 0; jj < 4; ++jj) {
;         kv[jj] = b2f(q_.rk[jj]);
;         kk[jj] = kv[jj] * kkme;
;         float ss = row_sum(kk[jj] * kk[jj]);
;         reinterpret_cast<float*>(IMG + IMG_PL)[128 + w4 * 16 + fq * 4 + jj] = ss;
;         lw[jj] = -0.8750360036f * sigmoidf_(w0c + cw[jj]);
;         ic[jj] = sigmoidf_(a0c + ca[jj]);
;       }
;       s4 lhi = pack4(lw[0], lw[1], lw[2], lw[3]);
;       s4 llo = pack4(lw[0] - b2f((u16)lhi[0]), lw[1] - b2f((u16)lhi[1]), lw[2] - b2f((u16)lhi[2]), lw[3] - b2f((u16)lhi[3]));
;       f32x4 cum = {0.f, 0.f, 0.f, 0.f};
;       cum = MFMA4(ltri, lhi, cum);
;       cum = MFMA4(ltri, llo, cum);
;       float bt[4], kt[4], ep3 = 0.f;
;       _Pragma("unroll") for (int jj = 0; jj < 4; ++jj) {
;         float ep = __builtin_amdgcn_exp2f(cum[jj]), em = __builtin_amdgcn_exp2f(-cum[jj]), ex = __builtin_amdgcn_exp2f(cum[jj] - lw[jj]);
;         float at = -kk[jj] * ex;
;         float rraw = b2f(q_.rr[jj]);
;         float rt = rraw * ep;
;         float kd = kv[jj] * (1.f + (ic[jj] - 1.f) * kac);
;         bt[jj] = kk[jj] * ic[jj] * em;
;         kt[jj] = kd * em;
;         int t = fq * 4 + jj, kc = w4 * 16 + fr;
;         float bsum = row_sum(rraw * kd * rkc);
.LBB0_2764:
	s_andn2_saveexec_b64 s[26:27], s[26:27]
	s_cbranch_execz .LBB0_2719
	v_add_u32_e32 v50, 3, v90
	v_cmp_gt_u32_e32 vcc, s2, v50
	s_and_saveexec_b64 s[30:31], vcc
	s_cbranch_execz .LBB0_2718
	ds_read_b128 v[58:61], v111
	ds_read_b128 v[234:237], v111 offset:2048
	ds_read_b128 v[238:241], v111 offset:1024
	ds_read_b128 v[242:245], v111 offset:3072
	s_mul_hi_u32 s62, s65, 0xaaaaaaab
	s_lshr_b32 s62, s62, 1
	s_mul_i32 s62, s62, 3
	v_subrev_u32_e32 v50, s62, v90
	s_waitcnt vmcnt(16) lgkmcnt(3)
	v_mfma_f32_16x16x32_bf16 v[8:11], v[8:11], v[58:61], 0
	s_mov_b32 s62, 0xbf60025c
	v_add_u32_e32 v50, 3, v50
	s_waitcnt lgkmcnt(2)
	v_mfma_f32_16x16x32_bf16 v[12:15], v[12:15], v[234:237], 0
	s_waitcnt lgkmcnt(1)
	v_mfma_f32_16x16x32_bf16 v[0:3], v[0:3], v[238:241], v[8:11]
	s_waitcnt lgkmcnt(0)
	v_mfma_f32_16x16x32_bf16 v[4:7], v[4:7], v[242:245], v[12:15]
	v_lshl_or_b32 v165, v219, 16, v218
	v_lshl_or_b32 v163, v221, 16, v220
	v_lshl_or_b32 v164, v223, 16, v222
	v_lshl_or_b32 v162, v225, 16, v224
	v_lshl_or_b32 v84, v227, 16, v226
	v_lshl_or_b32 v85, v229, 16, v228
	s_nop 1
	v_add_f32_e32 v0, v152, v0
	v_add_f32_e32 v1, v152, v1
	v_mul_f32_e32 v0, 0xbfb8aa3b, v0
	s_nop 2
	v_add_f32_e32 v4, v153, v4
	v_mul_f32_e32 v4, 0xbfb8aa3b, v4
	v_exp_f32_e32 v4, v4
	v_mul_f32_e32 v1, 0xbfb8aa3b, v1
	v_add_f32_e32 v2, v152, v2
	v_add_f32_e32 v3, v152, v3
	v_add_f32_e32 v4, 1.0, v4
	v_rcp_f32_e32 v10, v4
	v_add_f32_e32 v4, v153, v5
	v_mul_f32_e32 v4, 0xbfb8aa3b, v4
	v_exp_f32_e32 v4, v4
	v_exp_f32_e32 v0, v0
	v_exp_f32_e32 v1, v1
	v_mul_f32_e32 v2, 0xbfb8aa3b, v2
	v_add_f32_e32 v4, 1.0, v4
	v_rcp_f32_e32 v11, v4
	v_add_f32_e32 v4, v153, v6
	v_mul_f32_e32 v4, 0xbfb8aa3b, v4
	v_exp_f32_e32 v4, v4
	v_mul_f32_e32 v3, 0xbfb8aa3b, v3
	v_exp_f32_e32 v2, v2
	v_exp_f32_e32 v3, v3
	v_add_f32_e32 v4, 1.0, v4
	v_rcp_f32_e32 v6, v4
	v_add_f32_e32 v4, v153, v7
	v_add_f32_e32 v0, 1.0, v0
	v_add_f32_e32 v1, 1.0, v1
	v_mul_f32_e32 v4, 0xbfb8aa3b, v4
	v_rcp_f32_e32 v0, v0
	v_rcp_f32_e32 v1, v1
	v_add_f32_e32 v2, 1.0, v2
	v_add_f32_e32 v3, 1.0, v3
	v_exp_f32_e32 v4, v4
	v_rcp_f32_e32 v2, v2
	v_rcp_f32_e32 v3, v3
	v_pk_mul_f32 v[12:13], v[0:1], s[62:63] op_sel_hi:[1,0]
	v_add_f32_e32 v4, 1.0, v4
	v_rcp_f32_e32 v7, v4
	v_pk_mul_f32 v[14:15], v[2:3], s[62:63] op_sel_hi:[1,0]
	v_cvt_pk_bf16_f32 v4, v12, v13
	v_mad_u32_u24 v8, v50, s80, 0
	v_cvt_pk_bf16_f32 v5, v14, v15
	v_and_b32_e32 v51, 0xffff0000, v4
	v_lshlrev_b32_e32 v50, 16, v4
	v_pk_fma_f32 v[0:1], v[0:1], s[62:63], v[50:51] op_sel_hi:[1,0,1] neg_lo:[0,0,1] neg_hi:[0,0,1]
	v_and_b32_e32 v51, 0xffff0000, v5
	v_lshlrev_b32_e32 v50, 16, v5
	v_pk_fma_f32 v[2:3], v[2:3], s[62:63], v[50:51] op_sel_hi:[1,0,1] neg_lo:[0,0,1] neg_hi:[0,0,1]
	v_cvt_pk_bf16_f32 v50, v0, v1
	v_cvt_pk_bf16_f32 v51, v2, v3
	v_mfma_f32_16x16x16_bf16 v[0:3], v[72:73], v[4:5], 0
	v_add_u32_e32 v60, v8, v115
	v_add_u32_e32 v61, v60, v117
	v_add3_u32 v66, v8, v117, v115
	v_mfma_f32_16x16x16_bf16 v[2:5], v[72:73], v[50:51], v[0:3]
	v_add_u32_e32 v9, v8, v113
	v_add_u32_e32 v62, v9, v112
	v_lshl_add_u32 v63, v97, 2, v9
	s_nop 4
	v_sub_f32_e32 v0, v2, v12
	v_exp_f32_e32 v58, v2
	v_exp_f32_e64 v50, -v2
	v_exp_f32_e32 v59, v0
	v_exp_f32_e32 v67, v3
	v_exp_f32_e64 v51, -v3
	v_sub_f32_e32 v0, v3, v13
	v_and_b32_e32 v3, 0xffff0000, v165
	v_lshlrev_b32_e32 v2, 16, v165
	v_pk_mul_f32 v[54:55], v[76:77], v[2:3]
	v_exp_f32_e32 v68, v0
	v_pk_mul_f32 v[0:1], v[54:55], v[54:55]
	s_nop 1
	v_mov_b32_dpp v0, v0 quad_perm:[1,0,3,2] row_mask:0xf bank_mask:0xf bound_ctrl:1
	v_mov_b32_dpp v1, v1 quad_perm:[1,0,3,2] row_mask:0xf bank_mask:0xf bound_ctrl:1
	v_pk_fma_f32 v[0:1], v[54:55], v[54:55], v[0:1]
	s_nop 1
	v_mov_b32_dpp v12, v0 quad_perm:[2,3,0,1] row_mask:0xf bank_mask:0xf bound_ctrl:1
	v_mov_b32_dpp v13, v1 quad_perm:[2,3,0,1] row_mask:0xf bank_mask:0xf bound_ctrl:1
	v_pk_add_f32 v[0:1], v[0:1], v[12:13]
	s_nop 1
	v_mov_b32_dpp v12, v0 row_half_mirror row_mask:0xf bank_mask:0xf bound_ctrl:1
	v_mov_b32_dpp v13, v1 row_half_mirror row_mask:0xf bank_mask:0xf bound_ctrl:1
	v_pk_add_f32 v[0:1], v[0:1], v[12:13]
	s_nop 1
	v_mov_b32_dpp v12, v0 row_ror:8 row_mask:0xf bank_mask:0xf bound_ctrl:1
	v_mov_b32_dpp v13, v1 row_ror:8 row_mask:0xf bank_mask:0xf bound_ctrl:1
	v_pk_add_f32 v[12:13], v[0:1], v[12:13]
	v_mul_f32_e64 v0, v59, -v54
	v_cvt_pk_bf16_f32 v0, v0, s0
	ds_write_b16 v61, v0
	v_pk_mul_f32 v[0:1], v[54:55], v[10:11]
	v_pk_add_f32 v[10:11], v[10:11], -1.0 op_sel_hi:[1,0]
	v_pk_mul_f32 v[0:1], v[0:1], v[50:51]
	v_pk_fma_f32 v[10:11], v[74:75], v[10:11], 1.0 op_sel_hi:[1,1,0]
	v_cvt_pk_bf16_f32 v54, v0, s0
	v_pk_mul_f32 v[10:11], v[10:11], v[2:3]
	ds_write_b16 v66, v54 offset:4608
	v_pk_mul_f32 v[2:3], v[10:11], v[50:51]
	v_mul_f32_e64 v54, v68, -v55
	v_cvt_pk_bf16_f32 v50, v2, s0
	ds_write_b16 v66, v50 offset:6912
	v_lshlrev_b32_e32 v50, 16, v164
; __device__ __forceinline__ float b2f(u16 b) { return __uint_as_float(((unsigned)b) << 16); }
; __device__ __forceinline__ void scan_pc(const Params& p, int j, const u16* R, const u16* K, const u16* V, u16* Y, u16* YB) {
;     ...
;       _Pragma("unroll") for (int jj = 0; jj < 4; ++jj) {
;         float ep = __builtin_amdgcn_exp2f(cum[jj]), em = __builtin_amdgcn_exp2f(-cum[jj]), ex = __builtin_amdgcn_exp2f(cum[jj] - lw[jj]);
;         float at = -kk[jj] * ex;
;         float rraw = b2f(q_.rr[jj]);
;         float rt = rraw * ep;
;         float kd = kv[jj] * (1.f + (ic[jj] - 1.f) * kac);
;         bt[jj] = kk[jj] * ic[jj] * em;
;         kt[jj] = kd * em;
;         int t = fq * 4 + jj, kc = w4 * 16 + fr;
;         float bsum = row_sum(rraw * kd * rkc);
;         reinterpret_cast<float*>(IMG + IMG_PL)[64 + w4 * 16 + t] = bsum;
;         IMG[(0 * 16 + t) * XT_LD + kc] = f2b(at);
;         IMG[(1 * 16 + t) * XT_LD + kc] = f2b(rt);
;         IMG[(2 * 16 + t) * XT_LD + kc] = f2b(bt[jj]);
;         IMG[(3 * 16 + t) * XT_LD + kc] = f2b(kt[jj]);
;         if (jj == 3) ep3 = ep;
;       }
;       if (fq == 3) reinterpret_cast<float*>(IMG + IMG_PL)[w4 * 16 + fr] = ep3;
;       *reinterpret_cast<s4*>(IMG + IMG_XK + (0 * 64 + w4 * 16 + fr) * XK_LD + fq * 4) = pack4(bt[0], bt[1], bt[2], bt[3]);
;       *reinterpret_cast<s4*>(IMG + IMG_XK + (1 * 64 + w4 * 16 + fr) * XK_LD + fq * 4) = pack4(kt[0], kt[1], kt[2], kt[3]);
;       s4 vp; _Pragma("unroll") for (int jj = 0; jj < 4; ++jj) vp[jj] = (short)q_.rv[jj];
;       *reinterpret_cast<s4*>(IMG + IMG_VT + (w4 * 16 + fr) * XK_LD + fq * 4) = vp;
	v_and_b32_e32 v51, 0xffff0000, v164
	v_mul_f32_e32 v55, v58, v50
	v_cvt_pk_bf16_f32 v55, v55, s0
	v_pk_mul_f32 v[10:11], v[10:11], v[50:51]
	ds_write_b16 v66, v55 offset:2304
	v_mul_f32_e32 v55, v67, v51
	v_pk_mul_f32 v[50:51], v[78:79], v[10:11]
	v_exp_f32_e32 v66, v4
	s_nop 0
	v_mov_b32_dpp v50, v50 quad_perm:[1,0,3,2] row_mask:0xf bank_mask:0xf bound_ctrl:1
	v_mov_b32_dpp v51, v51 quad_perm:[1,0,3,2] row_mask:0xf bank_mask:0xf bound_ctrl:1
	v_pk_fma_f32 v[10:11], v[78:79], v[10:11], v[50:51]
	s_nop 1
	v_mov_b32_dpp v50, v10 quad_perm:[2,3,0,1] row_mask:0xf bank_mask:0xf bound_ctrl:1
	v_mov_b32_dpp v51, v11 quad_perm:[2,3,0,1] row_mask:0xf bank_mask:0xf bound_ctrl:1
	v_pk_add_f32 v[10:11], v[10:11], v[50:51]
	s_nop 1
	v_mov_b32_dpp v50, v10 row_half_mirror row_mask:0xf bank_mask:0xf bound_ctrl:1
	v_mov_b32_dpp v51, v11 row_half_mirror row_mask:0xf bank_mask:0xf bound_ctrl:1
	v_pk_add_f32 v[10:11], v[10:11], v[50:51]
	s_nop 1
	v_mov_b32_dpp v50, v10 row_ror:8 row_mask:0xf bank_mask:0xf bound_ctrl:1
	v_mov_b32_dpp v51, v11 row_ror:8 row_mask:0xf bank_mask:0xf bound_ctrl:1
	v_pk_add_f32 v[58:59], v[10:11], v[50:51]
	v_cvt_pk_bf16_f32 v10, v54, s0
	v_add_u32_e32 v11, v60, v120
	ds_write_b16 v11, v10
	v_cvt_pk_bf16_f32 v10, v55, s0
	v_add3_u32 v11, v8, v120, v115
	ds_write_b16 v11, v10 offset:2304
	v_cvt_pk_bf16_f32 v10, v1, s0
	v_exp_f32_e64 v50, -v4
	v_sub_f32_e32 v4, v4, v14
	v_and_b32_e32 v55, 0xffff0000, v163
	v_lshlrev_b32_e32 v54, 16, v163
	ds_write_b16 v11, v10 offset:4608
	v_cvt_pk_bf16_f32 v10, v3, s0
	v_exp_f32_e32 v67, v4
	v_sub_f32_e32 v4, v5, v15
	v_pk_mul_f32 v[60:61], v[76:77], v[54:55]
	ds_write_b16 v11, v10 offset:6912
	v_exp_f32_e32 v10, v5
	v_exp_f32_e64 v51, -v5
	v_exp_f32_e32 v68, v4
	v_pk_mul_f32 v[4:5], v[60:61], v[60:61]
	s_nop 1
	v_mov_b32_dpp v4, v4 quad_perm:[1,0,3,2] row_mask:0xf bank_mask:0xf bound_ctrl:1
	v_mov_b32_dpp v5, v5 quad_perm:[1,0,3,2] row_mask:0xf bank_mask:0xf bound_ctrl:1
	v_pk_fma_f32 v[4:5], v[60:61], v[60:61], v[4:5]
	s_nop 1
	v_mov_b32_dpp v14, v4 quad_perm:[2,3,0,1] row_mask:0xf bank_mask:0xf bound_ctrl:1
	v_mov_b32_dpp v15, v5 quad_perm:[2,3,0,1] row_mask:0xf bank_mask:0xf bound_ctrl:1
	v_pk_add_f32 v[4:5], v[4:5], v[14:15]
	s_nop 1
	v_mov_b32_dpp v14, v4 row_half_mirror row_mask:0xf bank_mask:0xf bound_ctrl:1
	v_mov_b32_dpp v15, v5 row_half_mirror row_mask:0xf bank_mask:0xf bound_ctrl:1
	v_pk_add_f32 v[4:5], v[4:5], v[14:15]
	s_nop 1
	v_mov_b32_dpp v14, v4 row_ror:8 row_mask:0xf bank_mask:0xf bound_ctrl:1
	v_mov_b32_dpp v15, v5 row_ror:8 row_mask:0xf bank_mask:0xf bound_ctrl:1
	v_pk_add_f32 v[14:15], v[4:5], v[14:15]
	v_mul_f32_e64 v4, v67, -v60
	v_cvt_pk_bf16_f32 v4, v4, s0
	ds_write_b16 v11, v4 offset:144
	v_pk_mul_f32 v[4:5], v[60:61], v[6:7]
	v_pk_add_f32 v[6:7], v[6:7], -1.0 op_sel_hi:[1,0]
	v_pk_mul_f32 v[4:5], v[4:5], v[50:51]
	ds_write_b128 v62, v[12:15] offset:17408
	v_cvt_pk_bf16_f32 v12, v4, s0
	v_pk_fma_f32 v[6:7], v[74:75], v[6:7], 1.0 op_sel_hi:[1,1,0]
	ds_write_b16 v11, v12 offset:4752
	v_pk_mul_f32 v[12:13], v[6:7], v[54:55]
	v_and_b32_e32 v15, 0xffff0000, v162
	v_pk_mul_f32 v[6:7], v[12:13], v[50:51]
	v_mul_f32_e64 v62, v68, -v61
	v_cvt_pk_bf16_f32 v14, v6, s0
	ds_write_b16 v11, v14 offset:7056
	v_lshlrev_b32_e32 v14, 16, v162
	v_mul_f32_e32 v50, v66, v14
	v_cvt_pk_bf16_f32 v50, v50, s0
	v_pk_mul_f32 v[12:13], v[12:13], v[14:15]
	ds_write_b16 v11, v50 offset:2448
	v_mul_f32_e32 v50, v10, v15
	v_pk_mul_f32 v[14:15], v[78:79], v[12:13]
	s_nop 1
	v_mov_b32_dpp v14, v14 quad_perm:[1,0,3,2] row_mask:0xf bank_mask:0xf bound_ctrl:1
	v_mov_b32_dpp v15, v15 quad_perm:[1,0,3,2] row_mask:0xf bank_mask:0xf bound_ctrl:1
	v_pk_fma_f32 v[12:13], v[78:79], v[12:13], v[14:15]
	s_nop 1
	v_mov_b32_dpp v14, v12 quad_perm:[2,3,0,1] row_mask:0xf bank_mask:0xf bound_ctrl:1
	v_mov_b32_dpp v15, v13 quad_perm:[2,3,0,1] row_mask:0xf bank_mask:0xf bound_ctrl:1
	v_pk_add_f32 v[12:13], v[12:13], v[14:15]
	s_nop 1
	v_mov_b32_dpp v14, v12 row_half_mirror row_mask:0xf bank_mask:0xf bound_ctrl:1
	v_mov_b32_dpp v15, v13 row_half_mirror row_mask:0xf bank_mask:0xf bound_ctrl:1
	v_pk_add_f32 v[12:13], v[12:13], v[14:15]
	s_nop 1
	v_mov_b32_dpp v14, v12 row_ror:8 row_mask:0xf bank_mask:0xf bound_ctrl:1
	v_mov_b32_dpp v15, v13 row_ror:8 row_mask:0xf bank_mask:0xf bound_ctrl:1
	v_pk_add_f32 v[60:61], v[12:13], v[14:15]
	v_cvt_pk_bf16_f32 v12, v62, s0
	ds_write_b16 v11, v12 offset:288
	v_cvt_pk_bf16_f32 v12, v50, s0
	ds_write_b16 v11, v12 offset:2592
	v_cvt_pk_bf16_f32 v12, v5, s0
	ds_write_b16 v11, v12 offset:4896
	v_cvt_pk_bf16_f32 v12, v7, s0
	ds_write_b128 v63, v[58:61] offset:17152
	ds_write_b16 v11, v12 offset:7200
	s_and_saveexec_b64 s[62:63], s[12:13]
	s_cbranch_execz .LBB0_2717
	v_lshl_add_u32 v9, v96, 2, v9
	ds_write_b32 v9, v10 offset:16896
	s_branch .LBB0_2717
